# NSA: softmax scale folded into q projection weights at PREP; Ot spilled to dead LDS across sel/win streams; reference max carried in QK MFMA C operand in window AND selected loops (no per-element add)
# speedup vs baseline: 1.0073x; 1.0057x over previous
.LBB0_394:
	v_lshlrev_b32_e32 v9, 16, v82
	v_lshlrev_b32_e32 v8, 16, v86
	v_mov_b32_e32 v24, v78
	v_mov_b32_e32 v25, v74
	v_pk_mul_f32 v[24:25], v[24:25], v[8:9]
	v_and_b32_e32 v11, 0xffff0000, v82
	v_sub_f32_e32 v0, v24, v25
	v_mov_b32_e32 v24, v74
	v_mov_b32_e32 v25, v78
	v_and_b32_e32 v10, 0xffff0000, v86
	v_pk_mul_f32 v[8:9], v[24:25], v[8:9]
	v_mov_b32_e32 v74, v79
	v_add_f32_e32 v5, v8, v9
	v_cmp_gt_u32_e32 vcc, 32, v185
	v_pk_mul_f32 v[8:9], v[74:75], v[10:11]
	v_mov_b32_e32 v78, v75
	v_cndmask_b32_e32 v0, v5, v0, vcc
	v_sub_f32_e32 v5, v8, v9
	v_pk_mul_f32 v[8:9], v[78:79], v[10:11]
	v_lshlrev_b32_e32 v13, 16, v83
	v_lshlrev_b32_e32 v12, 16, v87
	v_add_f32_e32 v7, v9, v8
	v_mov_b32_e32 v8, v80
	v_mov_b32_e32 v9, v76
	v_pk_mul_f32 v[8:9], v[8:9], v[12:13]
	v_cndmask_b32_e32 v5, v7, v5, vcc
	v_sub_f32_e32 v7, v8, v9
	v_mov_b32_e32 v8, v76
	v_mov_b32_e32 v9, v80
	v_pk_mul_f32 v[8:9], v[8:9], v[12:13]
	v_and_b32_e32 v15, 0xffff0000, v83
	v_and_b32_e32 v14, 0xffff0000, v87
	v_add_f32_e32 v8, v9, v8
	v_mov_b32_e32 v76, v81
	v_cndmask_b32_e32 v7, v8, v7, vcc
	v_pk_mul_f32 v[8:9], v[76:77], v[14:15]
	v_mov_b32_e32 v80, v77
	v_sub_f32_e32 v10, v8, v9
	v_pk_mul_f32 v[8:9], v[80:81], v[14:15]
	v_lshlrev_b32_e32 v17, 16, v84
	v_add_f32_e32 v8, v9, v8
	v_lshlrev_b32_e32 v16, 16, v88
	v_cndmask_b32_e32 v10, v8, v10, vcc
	v_mov_b32_e32 v8, v70
	v_mov_b32_e32 v9, v66
	v_pk_mul_f32 v[8:9], v[8:9], v[16:17]
	v_and_b32_e32 v19, 0xffff0000, v84
	v_sub_f32_e32 v11, v8, v9
	v_mov_b32_e32 v8, v66
	v_mov_b32_e32 v9, v70
	v_pk_mul_f32 v[8:9], v[8:9], v[16:17]
	v_and_b32_e32 v18, 0xffff0000, v88
	v_add_f32_e32 v8, v9, v8
	v_mov_b32_e32 v66, v71
	v_cndmask_b32_e32 v11, v8, v11, vcc
	v_pk_mul_f32 v[8:9], v[66:67], v[18:19]
	v_mov_b32_e32 v70, v67
	v_sub_f32_e32 v12, v8, v9
	v_pk_mul_f32 v[8:9], v[70:71], v[18:19]
	v_lshlrev_b32_e32 v21, 16, v85
	v_add_f32_e32 v8, v9, v8
	v_lshlrev_b32_e32 v20, 16, v89
	v_cndmask_b32_e32 v12, v8, v12, vcc
	v_mov_b32_e32 v8, v72
	v_mov_b32_e32 v9, v68
	v_pk_mul_f32 v[8:9], v[8:9], v[20:21]
	v_and_b32_e32 v23, 0xffff0000, v85
	v_sub_f32_e32 v13, v8, v9
	v_mov_b32_e32 v8, v68
	v_mov_b32_e32 v9, v72
	v_pk_mul_f32 v[8:9], v[8:9], v[20:21]
	v_and_b32_e32 v22, 0xffff0000, v89
	v_add_f32_e32 v8, v9, v8
	v_mov_b32_e32 v68, v73
	v_cndmask_b32_e32 v13, v8, v13, vcc
	v_pk_mul_f32 v[8:9], v[68:69], v[22:23]
	v_mov_b32_e32 v72, v69
	v_sub_f32_e32 v14, v8, v9
	v_pk_mul_f32 v[8:9], v[72:73], v[22:23]
	s_lshl_b32 s46, s75, 3
	v_add_f32_e32 v8, v9, v8
	s_add_i32 s46, s46, s74
	v_cndmask_b32_e32 v8, v8, v14, vcc
	v_mov_b32_e32 v81, 0
	v_cvt_pk_bf16_f32 v142, v0, v5
	v_cvt_pk_bf16_f32 v143, v7, v10
	v_cvt_pk_bf16_f32 v144, v11, v12
	v_cvt_pk_bf16_f32 v145, v13, v8
	s_cmp_gt_u32 s94, s80
	v_mov_b32_e32 v80, v81
	v_mov_b32_e32 v79, v81
	v_mov_b32_e32 v78, v81
	v_mov_b32_e32 v77, v81
	v_mov_b32_e32 v76, v81
	v_mov_b32_e32 v75, v81
	v_mov_b32_e32 v74, v81
	v_mov_b32_e32 v73, v81
	v_mov_b32_e32 v72, v81
	v_mov_b32_e32 v71, v81
	v_mov_b32_e32 v70, v81
	v_mov_b32_e32 v69, v81
	v_mov_b32_e32 v68, v81
	v_mov_b32_e32 v67, v81
	v_mov_b32_e32 v66, v81
	s_waitcnt vmcnt(6)
	v_mov_b32_e32 v97, v81
	v_mov_b32_e32 v96, v81
	v_mov_b32_e32 v95, v81
	v_mov_b32_e32 v94, v81
	v_mov_b32_e32 v93, v81
	v_mov_b32_e32 v92, v81
	v_mov_b32_e32 v91, v81
	v_mov_b32_e32 v90, v81
	v_mov_b32_e32 v89, v81
	v_mov_b32_e32 v88, v81
	v_mov_b32_e32 v87, v81
	v_mov_b32_e32 v86, v81
	v_mov_b32_e32 v85, v81
	v_mov_b32_e32 v84, v81
	v_mov_b32_e32 v83, v81
	v_mov_b32_e32 v82, v81
	v_mov_b32_e32 v201, v81
	s_cbranch_scc1 .LBB0_410
	v_lshrrev_b32_e32 v5, 3, v6
	v_lshlrev_b32_e32 v166, 4, v6
	v_and_b32_e32 v168, 4, v5
	v_ashrrev_i32_e32 v5, 31, v4
	v_mov_b32_e32 v201, 0
	v_lshlrev_b32_e32 v0, 4, v184
	v_and_b32_e32 v167, 0x3f0, v166
	s_mov_b32 s49, 0
	v_mov_b32_e32 v170, 0xf149f2ca
	v_lshlrev_b64 v[162:163], 1, v[2:3]
	v_lshlrev_b64 v[164:165], 1, v[4:5]
	v_mov_b32_e32 v82, 0
	v_mov_b32_e32 v83, v201
	v_mov_b32_e32 v84, v201
	v_mov_b32_e32 v85, v201
	v_mov_b32_e32 v86, v201
	v_mov_b32_e32 v87, v201
	v_mov_b32_e32 v88, v201
	v_mov_b32_e32 v89, v201
	v_mov_b32_e32 v90, v201
	v_mov_b32_e32 v91, v201
	v_mov_b32_e32 v92, v201
	v_mov_b32_e32 v93, v201
	v_mov_b32_e32 v94, v201
	v_mov_b32_e32 v95, v201
	v_mov_b32_e32 v96, v201
	v_mov_b32_e32 v97, v201
	v_mov_b32_e32 v66, v201
	v_mov_b32_e32 v67, v201
	v_mov_b32_e32 v68, v201
	v_mov_b32_e32 v69, v201
	v_mov_b32_e32 v70, v201
	v_mov_b32_e32 v71, v201
	v_mov_b32_e32 v72, v201
	v_mov_b32_e32 v73, v201
	v_mov_b32_e32 v74, v201
	v_mov_b32_e32 v75, v201
	v_mov_b32_e32 v76, v201
	v_mov_b32_e32 v77, v201
	v_mov_b32_e32 v78, v201
	v_mov_b32_e32 v79, v201
	v_mov_b32_e32 v80, v201
	v_mov_b32_e32 v81, v201
	s_waitcnt vmcnt(0)
	ds_write_b128 v166, v[98:101]
	ds_write_b128 v166, v[102:105] offset:4096
	ds_write_b128 v166, v[106:109] offset:8192
	ds_write_b128 v166, v[110:113] offset:12288
	s_mov_b32 s100, 0
	v_mov_b32_e32 v228, 0
	v_mov_b32_e32 v34, 0
	v_mov_b32_e32 v35, 0
	v_mov_b32_e32 v36, 0
	v_mov_b32_e32 v37, 0
	v_mov_b32_e32 v38, 0
	v_mov_b32_e32 v39, 0
	v_mov_b32_e32 v40, 0
	v_mov_b32_e32 v41, 0
	v_mov_b32_e32 v42, 0
	v_mov_b32_e32 v43, 0
	v_mov_b32_e32 v44, 0
	v_mov_b32_e32 v45, 0
	v_mov_b32_e32 v46, 0
	v_mov_b32_e32 v47, 0
	v_mov_b32_e32 v48, 0
	v_mov_b32_e32 v49, 0
	s_mov_b32 s101, 1

.Lmy_qk_s:
	v_cndmask_b32_e64 v50, v222, v34, s[40:41]
	v_cndmask_b32_e64 v51, v222, v35, s[40:41]
	v_cndmask_b32_e64 v52, v222, v36, s[40:41]
	v_cndmask_b32_e64 v53, v222, v37, s[40:41]
	v_cndmask_b32_e64 v54, v222, v38, s[40:41]
	v_cndmask_b32_e64 v55, v222, v39, s[40:41]
	v_cndmask_b32_e64 v56, v222, v40, s[40:41]
	v_cndmask_b32_e64 v57, v222, v41, s[40:41]
	v_cndmask_b32_e64 v58, v222, v42, s[40:41]
	v_cndmask_b32_e64 v59, v222, v43, s[40:41]
	v_cndmask_b32_e64 v60, v222, v44, s[40:41]
	v_cndmask_b32_e64 v61, v222, v45, s[40:41]
	v_cndmask_b32_e64 v62, v222, v46, s[40:41]
	v_cndmask_b32_e64 v63, v222, v47, s[40:41]
	v_cndmask_b32_e64 v64, v222, v48, s[40:41]
	v_cndmask_b32_e64 v65, v222, v49, s[40:41]
	v_add_u32_e32 v169, s52, v167
	ds_read_b128 v[2:5], v169
	ds_read_b128 v[114:117], v169 offset:1024
	ds_read_b128 v[118:121], v169 offset:2048
	ds_read_b128 v[122:125], v169 offset:3072
	ds_read_b128 v[6:9], v169 offset:4096
	ds_read_b128 v[126:129], v169 offset:5120
	ds_read_b128 v[146:149], v169 offset:6144
	ds_read_b128 v[172:175], v169 offset:7168
	s_waitcnt lgkmcnt(7)
	v_mfma_f32_32x32x16_bf16 v[18:33], v[2:5], v[142:145], v[50:65]
	s_waitcnt lgkmcnt(3)
	v_mfma_f32_32x32x16_bf16 v[2:17], v[6:9], v[142:145], v[50:65]
	v_mfma_f32_32x32x16_bf16 v[18:33], v[114:117], v[130:133], v[18:33]
	s_waitcnt lgkmcnt(2)
	v_mfma_f32_32x32x16_bf16 v[2:17], v[126:129], v[130:133], v[2:17]
	v_mfma_f32_32x32x16_bf16 v[18:33], v[118:121], v[134:137], v[18:33]
	s_waitcnt lgkmcnt(1)
	v_mfma_f32_32x32x16_bf16 v[2:17], v[146:149], v[134:137], v[2:17]
	v_mfma_f32_32x32x16_bf16 v[18:33], v[122:125], v[138:141], v[18:33]
	ds_read_b128 v[158:161], v169 offset:8192
	ds_read_b128 v[154:157], v169 offset:9216
	ds_read_b128 v[150:153], v169 offset:10240
	ds_read_b128 v[146:149], v169 offset:11264
	ds_read_b128 v[126:129], v169 offset:12288
	ds_read_b128 v[122:125], v169 offset:13312
	ds_read_b128 v[118:121], v169 offset:14336
	ds_read_b128 v[114:117], v169 offset:15360
	s_waitcnt lgkmcnt(8)
	v_mfma_f32_32x32x16_bf16 v[2:17], v[172:175], v[138:141], v[2:17]
	s_lshl_b32 s0, s94, 6
	s_or_b32 s12, s0, 63
	s_cmp_le_i32 s12, s46
	s_cbranch_scc1 .LBB0_405
	v_or_b32_e32 v169, s0, v168
	v_or_b32_e32 v171, 32, v169
	v_cmp_le_i32_e32 vcc, v169, v200
	v_or_b32_e32 v172, 34, v169
	s_nop 0
	v_cndmask_b32_e32 v18, v222, v18, vcc
	v_cmp_le_i32_e32 vcc, v171, v200
	v_or_b32_e32 v171, 33, v169
	s_nop 0
	v_cndmask_b32_e32 v2, v222, v2, vcc
	v_cmp_lt_i32_e32 vcc, v169, v200
	s_nop 1
	v_cndmask_b32_e32 v19, v222, v19, vcc
	v_cmp_le_i32_e32 vcc, v171, v200
	v_or_b32_e32 v171, 2, v169
	s_nop 0
	v_cndmask_b32_e32 v3, v222, v3, vcc
	v_cmp_le_i32_e32 vcc, v171, v200
	v_or_b32_e32 v171, 3, v169
	s_nop 0
	v_cndmask_b32_e32 v20, v222, v20, vcc
	v_cmp_le_i32_e32 vcc, v172, v200
	v_or_b32_e32 v172, 35, v169
	s_nop 0
	v_cndmask_b32_e32 v4, v222, v4, vcc
	v_cmp_le_i32_e32 vcc, v171, v200
	v_or_b32_e32 v171, 8, v169
	s_nop 0
	v_cndmask_b32_e32 v21, v222, v21, vcc
	v_cmp_le_i32_e32 vcc, v172, v200
	v_or_b32_e32 v172, 40, v169
	s_nop 0
	v_cndmask_b32_e32 v5, v222, v5, vcc
	v_cmp_le_i32_e32 vcc, v171, v200
	v_or_b32_e32 v171, 9, v169
	s_nop 0
	v_cndmask_b32_e32 v22, v222, v22, vcc
	v_cmp_le_i32_e32 vcc, v172, v200
	v_or_b32_e32 v172, 41, v169
	s_nop 0
	v_cndmask_b32_e32 v6, v222, v6, vcc
	v_cmp_le_i32_e32 vcc, v171, v200
	v_or_b32_e32 v171, 10, v169
	s_nop 0
	v_cndmask_b32_e32 v23, v222, v23, vcc
	v_cmp_le_i32_e32 vcc, v172, v200
	v_or_b32_e32 v172, 42, v169
	s_nop 0
	v_cndmask_b32_e32 v7, v222, v7, vcc
	v_cmp_le_i32_e32 vcc, v171, v200
	v_or_b32_e32 v171, 11, v169
	s_nop 0
	v_cndmask_b32_e32 v24, v222, v24, vcc
	v_cmp_le_i32_e32 vcc, v172, v200
	v_or_b32_e32 v172, 43, v169
	s_nop 0
	v_cndmask_b32_e32 v8, v222, v8, vcc
	v_cmp_le_i32_e32 vcc, v171, v200
	v_or_b32_e32 v171, 16, v169
	s_nop 0
	v_cndmask_b32_e32 v25, v222, v25, vcc
	v_cmp_le_i32_e32 vcc, v172, v200
	v_or_b32_e32 v172, 48, v169
	s_nop 0
	v_cndmask_b32_e32 v9, v222, v9, vcc
	v_cmp_le_i32_e32 vcc, v171, v200
	v_or_b32_e32 v171, 17, v169
	s_nop 0
	v_cndmask_b32_e32 v26, v222, v26, vcc
	v_cmp_le_i32_e32 vcc, v172, v200
	v_or_b32_e32 v172, 49, v169
	s_nop 0
	v_cndmask_b32_e32 v10, v222, v10, vcc
	v_cmp_le_i32_e32 vcc, v171, v200
	v_or_b32_e32 v171, 18, v169
	s_nop 0
	v_cndmask_b32_e32 v27, v222, v27, vcc
	v_cmp_le_i32_e32 vcc, v172, v200
	v_or_b32_e32 v172, 50, v169
	s_nop 0
	v_cndmask_b32_e32 v11, v222, v11, vcc
	v_cmp_le_i32_e32 vcc, v171, v200
	v_or_b32_e32 v171, 19, v169
	s_nop 0
	v_cndmask_b32_e32 v28, v222, v28, vcc
	v_cmp_le_i32_e32 vcc, v172, v200
	v_or_b32_e32 v172, 51, v169
	s_nop 0
	v_cndmask_b32_e32 v12, v222, v12, vcc
	v_cmp_le_i32_e32 vcc, v171, v200
	v_or_b32_e32 v171, 24, v169
	s_nop 0
	v_cndmask_b32_e32 v29, v222, v29, vcc
	v_cmp_le_i32_e32 vcc, v172, v200
	v_or_b32_e32 v172, 56, v169
	s_nop 0
	v_cndmask_b32_e32 v13, v222, v13, vcc
	v_cmp_le_i32_e32 vcc, v171, v200
	v_or_b32_e32 v171, 25, v169
	s_nop 0
	v_cndmask_b32_e32 v30, v222, v30, vcc
	v_cmp_le_i32_e32 vcc, v172, v200
	v_or_b32_e32 v172, 57, v169
	s_nop 0
	v_cndmask_b32_e32 v14, v222, v14, vcc
	v_cmp_le_i32_e32 vcc, v171, v200
	v_or_b32_e32 v171, 26, v169
	s_nop 0
	v_cndmask_b32_e32 v31, v222, v31, vcc
	v_cmp_le_i32_e32 vcc, v172, v200
	v_or_b32_e32 v172, 58, v169
	s_nop 0
	v_cndmask_b32_e32 v15, v222, v15, vcc
	v_cmp_le_i32_e32 vcc, v171, v200
	v_or_b32_e32 v171, 27, v169
	v_or_b32_e32 v169, 59, v169
	v_cndmask_b32_e32 v32, v222, v32, vcc
	v_cmp_le_i32_e32 vcc, v172, v200
	s_nop 1
	v_cndmask_b32_e32 v16, v222, v16, vcc
	v_cmp_le_i32_e32 vcc, v171, v200
	s_nop 1
	v_cndmask_b32_e32 v33, v222, v33, vcc
	v_cmp_le_i32_e32 vcc, v169, v200
	s_nop 1
	v_cndmask_b32_e32 v17, v222, v17, vcc
.LBB0_405:
	s_cmp_eq_u32 s101, 0
	s_cbranch_scc1 .LBB0_407
	v_max3_f32 v169, v18, v19, v20
	v_max3_f32 v171, v21, v22, v23
	v_max3_f32 v172, v24, v25, v26
	v_max3_f32 v169, v169, v27, v28
	v_max3_f32 v171, v171, v29, v30
	v_max3_f32 v172, v172, v31, v32
	v_max3_f32 v169, v169, v171, v33
	v_max_f32_e32 v169, v169, v172
	v_max3_f32 v171, v2, v3, v4
	v_max3_f32 v172, v5, v6, v7
	v_max3_f32 v173, v8, v9, v10
	v_max3_f32 v171, v171, v11, v12
	v_max3_f32 v172, v172, v13, v14
	v_max3_f32 v173, v173, v15, v16
	v_max3_f32 v171, v171, v172, v17
	v_max3_f32 v169, v169, v171, v173
	v_cndmask_b32_e64 v169, v222, v169, s[40:41]
	v_mov_b32_e32 v171, v169
	s_nop 1
	v_permlane32_swap_b32_e32 v169, v171
	v_max_f32_e32 v169, v169, v171
	v_add_f32_e32 v169, v169, v228
	v_max_f32_e32 v169, v170, v169
	v_add_f32_e32 v171, 0x41000000, v170
	v_cmp_gt_f32_e32 vcc, v169, v171
	s_cbranch_vccz .Lmy_s_noslow
	v_sub_f32_e32 v226, v170, v169
	v_exp_f32_e32 v226, v226
	s_nop 0
	v_mul_f32_e32 v201, v201, v226
	v_pk_mul_f32 v[80:81], v[80:81], v[226:227] op_sel_hi:[1,0]
	v_pk_mul_f32 v[78:79], v[78:79], v[226:227] op_sel_hi:[1,0]
	v_pk_mul_f32 v[76:77], v[76:77], v[226:227] op_sel_hi:[1,0]
	v_pk_mul_f32 v[74:75], v[74:75], v[226:227] op_sel_hi:[1,0]
	v_pk_mul_f32 v[72:73], v[72:73], v[226:227] op_sel_hi:[1,0]
	v_pk_mul_f32 v[70:71], v[70:71], v[226:227] op_sel_hi:[1,0]
	v_pk_mul_f32 v[68:69], v[68:69], v[226:227] op_sel_hi:[1,0]
	v_pk_mul_f32 v[66:67], v[66:67], v[226:227] op_sel_hi:[1,0]
	v_pk_mul_f32 v[96:97], v[96:97], v[226:227] op_sel_hi:[1,0]
	v_pk_mul_f32 v[94:95], v[94:95], v[226:227] op_sel_hi:[1,0]
	v_pk_mul_f32 v[92:93], v[92:93], v[226:227] op_sel_hi:[1,0]
	v_pk_mul_f32 v[90:91], v[90:91], v[226:227] op_sel_hi:[1,0]
	v_pk_mul_f32 v[88:89], v[88:89], v[226:227] op_sel_hi:[1,0]
	v_pk_mul_f32 v[86:87], v[86:87], v[226:227] op_sel_hi:[1,0]
	v_pk_mul_f32 v[84:85], v[84:85], v[226:227] op_sel_hi:[1,0]
	v_pk_mul_f32 v[82:83], v[82:83], v[226:227] op_sel_hi:[1,0]
	v_mov_b32_e32 v170, v169
	v_cmp_lt_f32_e32 vcc, 0xf0a18f08, v169
	s_nop 1
	v_cndmask_b32_e32 v213, 0, v169, vcc
	v_sub_f32_e32 v229, v213, v228
	v_mov_b32_e32 v228, v213
	v_sub_f32_e32 v34, 0, v213
	v_sub_f32_e32 v35, 0, v213
	v_sub_f32_e32 v36, 0, v213
	v_sub_f32_e32 v37, 0, v213
	v_sub_f32_e32 v38, 0, v213
	v_sub_f32_e32 v39, 0, v213
	v_sub_f32_e32 v40, 0, v213
	v_sub_f32_e32 v41, 0, v213
	v_sub_f32_e32 v42, 0, v213
	v_sub_f32_e32 v43, 0, v213
	v_sub_f32_e32 v44, 0, v213
	v_sub_f32_e32 v45, 0, v213
	v_sub_f32_e32 v46, 0, v213
	v_sub_f32_e32 v47, 0, v213
	v_sub_f32_e32 v48, 0, v213
	v_sub_f32_e32 v49, 0, v213
	v_sub_f32_e32 v2, v2, v229
	v_sub_f32_e32 v3, v3, v229
	v_sub_f32_e32 v4, v4, v229
	v_sub_f32_e32 v5, v5, v229
	v_sub_f32_e32 v6, v6, v229
	v_sub_f32_e32 v7, v7, v229
	v_sub_f32_e32 v8, v8, v229
	v_sub_f32_e32 v9, v9, v229
	v_sub_f32_e32 v10, v10, v229
	v_sub_f32_e32 v11, v11, v229
	v_sub_f32_e32 v12, v12, v229
	v_sub_f32_e32 v13, v13, v229
	v_sub_f32_e32 v14, v14, v229
	v_sub_f32_e32 v15, v15, v229
	v_sub_f32_e32 v16, v16, v229
	v_sub_f32_e32 v17, v17, v229
	v_sub_f32_e32 v18, v18, v229
	v_sub_f32_e32 v19, v19, v229
	v_sub_f32_e32 v20, v20, v229
	v_sub_f32_e32 v21, v21, v229
	v_sub_f32_e32 v22, v22, v229
	v_sub_f32_e32 v23, v23, v229
	v_sub_f32_e32 v24, v24, v229
	v_sub_f32_e32 v25, v25, v229
	v_sub_f32_e32 v26, v26, v229
	v_sub_f32_e32 v27, v27, v229
	v_sub_f32_e32 v28, v28, v229
	v_sub_f32_e32 v29, v29, v229
	v_sub_f32_e32 v30, v30, v229
	v_sub_f32_e32 v31, v31, v229
	v_sub_f32_e32 v32, v32, v229
	v_sub_f32_e32 v33, v33, v229
.Lmy_s_noslow:
	v_cmp_gt_f32_e32 vcc, 0xf0a18f08, v170
	s_nop 1
	s_cmp_lg_u64 vcc, 0
	s_cselect_b32 s100, 1, 0
.LBB0_407:
	s_nop 1
	v_exp_f32_e32 v18, v18
	v_exp_f32_e32 v2, v2
	v_exp_f32_e32 v19, v19
	v_exp_f32_e32 v3, v3
	v_add_f32_e32 v177, v18, v2
	v_exp_f32_e32 v20, v20
	v_exp_f32_e32 v4, v4
	v_add_f32_e32 v176, v19, v3
	v_add_f32_e32 v177, v176, v177
	v_exp_f32_e32 v21, v21
	v_exp_f32_e32 v5, v5
	v_add_f32_e32 v176, v20, v4
	v_add_f32_e32 v177, v176, v177
	v_exp_f32_e32 v22, v22
	v_exp_f32_e32 v6, v6
	v_add_f32_e32 v176, v21, v5
	v_add_f32_e32 v177, v176, v177
	v_exp_f32_e32 v23, v23
	v_exp_f32_e32 v7, v7
	v_add_f32_e32 v176, v22, v6
	v_add_f32_e32 v177, v176, v177
	v_exp_f32_e32 v24, v24
	v_exp_f32_e32 v8, v8
	v_add_f32_e32 v176, v23, v7
	v_add_f32_e32 v177, v176, v177
	v_exp_f32_e32 v25, v25
	v_exp_f32_e32 v9, v9
	v_add_f32_e32 v176, v24, v8
	v_add_f32_e32 v177, v176, v177
	v_exp_f32_e32 v26, v26
	v_exp_f32_e32 v10, v10
	v_add_f32_e32 v176, v25, v9
	v_add_f32_e32 v177, v176, v177
	v_exp_f32_e32 v27, v27
	v_exp_f32_e32 v11, v11
	v_add_f32_e32 v176, v26, v10
	v_add_f32_e32 v177, v176, v177
	v_exp_f32_e32 v28, v28
	v_exp_f32_e32 v12, v12
	v_add_f32_e32 v176, v27, v11
	v_add_f32_e32 v177, v176, v177
	v_exp_f32_e32 v29, v29
	v_exp_f32_e32 v13, v13
	v_add_f32_e32 v176, v28, v12
	v_add_f32_e32 v177, v176, v177
	v_exp_f32_e32 v30, v30
	v_exp_f32_e32 v14, v14
	v_add_f32_e32 v176, v29, v13
	v_add_f32_e32 v177, v176, v177
	v_exp_f32_e32 v31, v31
	v_exp_f32_e32 v15, v15
	v_add_f32_e32 v176, v30, v14
	v_add_f32_e32 v177, v176, v177
	v_exp_f32_e32 v32, v32
	v_exp_f32_e32 v16, v16
	v_add_f32_e32 v176, v31, v15
	v_add_f32_e32 v177, v176, v177
	v_exp_f32_e32 v33, v33
	v_exp_f32_e32 v17, v17
	v_add_f32_e32 v176, v32, v16
	v_add_f32_e32 v177, v176, v177
	v_add_f32_e32 v176, v33, v17
	v_add_f32_e32 v177, v176, v177
	v_cmp_lt_f32_e32 vcc, 0x47800000, v177
	s_cbranch_vccnz .Lmy_rd_s
.Lmy_nrd_s:
	v_cvt_pk_bf16_f32 v172, v18, v19
	v_cvt_pk_bf16_f32 v173, v20, v21
	v_cvt_pk_bf16_f32 v174, v22, v23
	v_cvt_pk_bf16_f32 v175, v24, v25
	v_cvt_pk_bf16_f32 v9, v8, v9
	v_cvt_pk_bf16_f32 v8, v6, v7
	s_waitcnt lgkmcnt(0)
	v_mfma_f32_32x32x16_bf16 v[82:97], v[158:161], v[172:175], v[82:97]
	v_cvt_pk_bf16_f32 v7, v4, v5
	v_cvt_pk_bf16_f32 v6, v2, v3
	v_mfma_f32_32x32x16_bf16 v[66:81], v[126:129], v[172:175], v[66:81]
	v_cvt_pk_bf16_f32 v2, v10, v11
	v_cvt_pk_bf16_f32 v3, v12, v13
	v_cvt_pk_bf16_f32 v4, v14, v15
	v_cvt_pk_bf16_f32 v5, v16, v17
	v_cvt_pk_bf16_f32 v10, v26, v27
	v_cvt_pk_bf16_f32 v11, v28, v29
	v_cvt_pk_bf16_f32 v12, v30, v31
	v_cvt_pk_bf16_f32 v13, v32, v33
	v_add_f32_e32 v201, v177, v201
	s_nop 0
	v_mfma_f32_32x32x16_bf16 v[82:97], v[154:157], v[10:13], v[82:97]
	v_mfma_f32_32x32x16_bf16 v[66:81], v[122:125], v[10:13], v[66:81]
	v_mfma_f32_32x32x16_bf16 v[82:97], v[150:153], v[6:9], v[82:97]
	v_mfma_f32_32x32x16_bf16 v[66:81], v[118:121], v[6:9], v[66:81]
	v_mfma_f32_32x32x16_bf16 v[82:97], v[146:149], v[2:5], v[82:97]
	v_mfma_f32_32x32x16_bf16 v[66:81], v[114:117], v[2:5], v[66:81]
	s_mov_b32 s101, s100
	s_xor_b32 s49, s49, 1
	s_cmp_le_i32 s1, s80
	s_cbranch_scc1 .LBB0_409
	s_branch .LBB0_410
.LBB0_408:
	s_xor_b32 s49, s49, 1
	s_cmp_le_i32 s1, s80
	s_cbranch_scc0 .LBB0_410
.LBB0_409:
	s_mov_b32 s94, s1
	s_branch .LBB0_396
.Lmy_rd_s:
	s_cmp_eq_u32 s101, 1
	s_cbranch_scc1 .Lmy_nrd_s
	s_mov_b32 s101, 1
	s_branch .Lmy_qk_s
